# retention w_out GEMM residual epilogue: same rolling prefetch of the X read-modify-write loads as the FFN down GEMM
# speedup vs baseline: 1.0129x; 1.0023x over previous
; __device__ __forceinline__ void store8bf(bf16_t* p, f32x4 a, f32x4 b) { u32x4 w; w.x = pk2(a[0], a[1]); w.y = pk2(a[2], a[3]); w.z = pk2(b[0], b[1]); w.w = pk2(b[2], b[3]); *(u32x4*)p = w; }
; __device__ __forceinline__ float sigmoid_f(float v) { return 1.0f / (1.0f + __expf(-v)); }
;     __device__ __forceinline__ void operator()(const f32x4 (&acc)[2][2][4][2], const pg8::Unit& u, int wr, int wc, int fr, int fq) const {
;     ...
;         const int rowb = u.pm * 256 + wr * 64 + fr, colb = u.pn * (GLU ? 128 : 256) + wc * 32 + 8 * fq;
; #pragma unroll
;         for (int ai = 0; ai < 2; ++ai)
; #pragma unroll
;             for (int m = 0; m < 4; ++m) {
;                 const int t = rowb + ai * 128 + m * 16; float ss = 0.f;
;                 float* xr = X + (size_t)t * D + colb; bf16_t* xbr = XB + (size_t)t * D + colb;
;                 if (GLU) {
;                     f32x4 y0, y1;
; #pragma unroll
;                     for (int jj = 0; jj < 4; ++jj) { y0[jj] = acc[ai][0][m][0][jj] * sigmoid_f(acc[ai][1][m][0][jj]); y1[jj] = acc[ai][0][m][1][jj] * sigmoid_f(acc[ai][1][m][1][jj]); }
;                     const f32x4 x0 = *(const f32x4*)xr + y0, x1 = *(const f32x4*)(xr + 4) + y1;
;                     if (!dry) { *(f32x4*)xr = x0; *(f32x4*)(xr + 4) = x1; store8bf(xbr, x0, x1); }
;                     ss += (x0[0] * x0[0] + x0[1] * x0[1]) + (x0[2] * x0[2] + x0[3] * x0[3]) + (x1[0] * x1[0] + x1[1] * x1[1]) + (x1[2] * x1[2] + x1[3] * x1[3]);
;                 } else {
; #pragma unroll
;                     for (int bj = 0; bj < 2; ++bj) {
;                         const f32x4 x0 = *(const f32x4*)(xr + bj * 128) + acc[ai][bj][m][0], x1 = *(const f32x4*)(xr + bj * 128 + 4) + acc[ai][bj][m][1];
;                         if (!dry) { *(f32x4*)(xr + bj * 128) = x0; *(f32x4*)(xr + bj * 128 + 4) = x1; store8bf(xbr + bj * 128, x0, x1); }
;                         ss += (x0[0] * x0[0] + x0[1] * x0[1]) + (x0[2] * x0[2] + x0[3] * x0[3]) + (x1[0] * x1[0] + x1[1] * x1[1]) + (x1[2] * x1[2] + x1[3] * x1[3]);
;                     }
;                 }
;                 ss += __shfl_xor(ss, 16); ss += __shfl_xor(ss, 32);
;                 if (fq == 0 && !dry) rsp_next[(size_t)t * 64 + u.pn * 4 + wc] = ss;
;             }
.LBB0_896:
	v_ashrrev_i32_e32 v139, 31, v138
	v_and_b32_e32 v145, 64, v229
	v_lshl_add_u64 v[142:143], v[138:139], 2, s[26:27]
	v_lshl_add_u64 v[140:141], v[138:139], 1, s[24:25]
	v_xor_b32_e32 v139, 16, v229
	v_add_u32_e32 v145, 64, v145
	v_cmp_lt_i32_e32 vcc, v139, v145
	v_lshl_add_u32 v144, s8, 8, v148
	s_nop 0
	v_cndmask_b32_e32 v139, v229, v139, vcc
	v_lshlrev_b32_e32 v153, 2, v139
	v_xor_b32_e32 v139, 32, v229
	v_cmp_lt_i32_e32 vcc, v139, v145
	v_ashrrev_i32_e32 v145, 31, v144
	v_lshlrev_b64 v[146:147], 13, v[144:145]
	v_lshl_add_u64 v[146:147], v[142:143], 0, v[146:147]
	v_lshlrev_b64 v[154:155], 12, v[144:145]
	v_lshl_add_u64 v[166:167], v[140:141], 0, v[154:155]
	v_mov_b64_e32 v[216:217], v[146:147]
	s_mov_b32 s101, 0
	global_load_dwordx4 v[170:173], v[216:217], off offset:16
	global_load_dwordx4 v[174:177], v[216:217], off
	s_mov_b32 s100, 0x200
	v_lshl_add_u64 v[190:191], v[216:217], 0, s[100:101]
	global_load_dwordx4 v[178:181], v[190:191], off offset:16
	global_load_dwordx4 v[182:185], v[190:191], off
	s_mov_b32 s100, 0x20000
	v_lshl_add_u64 v[190:191], v[216:217], 0, s[100:101]
	global_load_dwordx4 v[186:189], v[190:191], off offset:16
	global_load_dwordx4 v[196:199], v[190:191], off
	s_mov_b32 s100, 0x20200
	v_lshl_add_u64 v[190:191], v[216:217], 0, s[100:101]
	global_load_dwordx4 v[200:203], v[190:191], off offset:16
	global_load_dwordx4 v[204:207], v[190:191], off
	s_mov_b32 s100, 0x40000
	v_lshl_add_u64 v[190:191], v[216:217], 0, s[100:101]
	global_load_dwordx4 v[208:211], v[190:191], off offset:16
	global_load_dwordx4 v[212:215], v[190:191], off
	s_mov_b32 s100, 0x40200
	v_lshl_add_u64 v[190:191], v[216:217], 0, s[100:101]
	global_load_dwordx4 v[224:227], v[190:191], off offset:16
	global_load_dwordx4 v[236:239], v[190:191], off
	s_mov_b32 s100, 0x60000
	v_lshl_add_u64 v[190:191], v[216:217], 0, s[100:101]
	global_load_dwordx4 v[240:243], v[190:191], off offset:16
	global_load_dwordx4 v[244:247], v[190:191], off
	s_waitcnt vmcnt(12)
	v_mov_b64_e32 v[154:155], v[170:171]
	v_mov_b64_e32 v[156:157], v[172:173]
	v_mov_b64_e32 v[158:159], v[174:175]
	v_mov_b64_e32 v[160:161], v[176:177]
	v_cndmask_b32_e32 v139, v229, v139, vcc
	v_lshlrev_b32_e32 v139, 2, v139
	v_pk_add_f32 v[156:157], v[122:123], v[156:157]
	v_pk_add_f32 v[160:161], v[126:127], v[160:161]
	v_pk_add_f32 v[158:159], v[124:125], v[158:159]
	v_pk_add_f32 v[154:155], v[120:121], v[154:155]
	global_store_dwordx4 v[146:147], v[158:161], off
	global_store_dwordx4 v[146:147], v[154:157], off offset:16
	s_mov_b32 s100, 0x60200
	v_lshl_add_u64 v[190:191], v[216:217], 0, s[100:101]
	global_load_dwordx4 v[170:173], v[190:191], off offset:16
	global_load_dwordx4 v[174:177], v[190:191], off
	v_cvt_pk_bf16_f32 v162, v158, v159
	v_mul_f32_e32 v159, v159, v159
	v_fmac_f32_e32 v159, v158, v158
	v_mul_f32_e32 v158, v161, v161
	v_cvt_pk_bf16_f32 v164, v154, v155
	v_fmac_f32_e32 v158, v160, v160
	v_mul_f32_e32 v155, v155, v155
	v_add_f32_e32 v158, v159, v158
	v_fmac_f32_e32 v155, v154, v154
	v_cvt_pk_bf16_f32 v163, v160, v161
	v_cvt_pk_bf16_f32 v165, v156, v157
	v_add_f32_e32 v154, v158, v155
	v_mul_f32_e32 v155, v157, v157
	global_store_dwordx4 v[166:167], v[162:165], off
	v_fmac_f32_e32 v155, v156, v156
	v_add_f32_e32 v168, v155, v154
	s_waitcnt vmcnt(15)
	v_mov_b64_e32 v[154:155], v[178:179]
	v_mov_b64_e32 v[156:157], v[180:181]
	v_mov_b64_e32 v[158:159], v[182:183]
	v_mov_b64_e32 v[160:161], v[184:185]
	v_pk_add_f32 v[156:157], v[106:107], v[156:157]
	v_pk_add_f32 v[160:161], v[110:111], v[160:161]
	v_pk_add_f32 v[158:159], v[108:109], v[158:159]
	v_pk_add_f32 v[154:155], v[104:105], v[154:155]
	global_store_dwordx4 v[146:147], v[158:161], off offset:512
	global_store_dwordx4 v[146:147], v[154:157], off offset:528
	s_mov_b32 s100, 0x100000
	v_lshl_add_u64 v[190:191], v[216:217], 0, s[100:101]
	global_load_dwordx4 v[178:181], v[190:191], off offset:16
	global_load_dwordx4 v[182:185], v[190:191], off
	v_mul_f32_e32 v146, v159, v159
	v_mul_f32_e32 v147, v161, v161
	v_fmac_f32_e32 v146, v158, v158
	v_fmac_f32_e32 v147, v160, v160
	v_add_f32_e32 v146, v146, v147
	v_mul_f32_e32 v147, v155, v155
	v_fmac_f32_e32 v147, v154, v154
	v_add_f32_e32 v146, v146, v147
	v_mul_f32_e32 v147, v157, v157
	v_fmac_f32_e32 v147, v156, v156
	v_add_f32_e32 v146, v147, v146
	v_add_f32_e32 v146, v168, v146
	ds_bpermute_b32 v147, v153, v146
	v_cvt_pk_bf16_f32 v162, v158, v159
	v_cvt_pk_bf16_f32 v163, v160, v161
	v_cvt_pk_bf16_f32 v164, v154, v155
	v_cvt_pk_bf16_f32 v165, v156, v157
	s_waitcnt lgkmcnt(0)
	v_add_f32_e32 v146, v146, v147
	ds_bpermute_b32 v147, v139, v146
	global_store_dwordx4 v[166:167], v[162:165], off offset:256
	s_and_saveexec_b64 s[4:5], s[6:7]
	s_cbranch_execz .LBB0_898
	s_waitcnt lgkmcnt(0)
	v_add_f32_e32 v154, v146, v147
	s_lshl_b32 s14, s10, 2
	v_lshlrev_b64 v[146:147], 8, v[144:145]
	s_ashr_i32 s15, s14, 31
	v_lshl_add_u64 v[146:147], s[18:19], 0, v[146:147]
	v_lshl_add_u64 v[146:147], s[14:15], 2, v[146:147]
	s_lshl_b32 s68, s64, 2
	v_lshl_add_u64 v[146:147], v[146:147], 0, s[68:69]
	global_store_dword v[146:147], v154, off
; __device__ __forceinline__ void store8bf(bf16_t* p, f32x4 a, f32x4 b) { u32x4 w; w.x = pk2(a[0], a[1]); w.y = pk2(a[2], a[3]); w.z = pk2(b[0], b[1]); w.w = pk2(b[2], b[3]); *(u32x4*)p = w; }
; __device__ __forceinline__ float sigmoid_f(float v) { return 1.0f / (1.0f + __expf(-v)); }
;     __device__ __forceinline__ void operator()(const f32x4 (&acc)[2][2][4][2], const pg8::Unit& u, int wr, int wc, int fr, int fq) const {
;     ...
;         const int rowb = u.pm * 256 + wr * 64 + fr, colb = u.pn * (GLU ? 128 : 256) + wc * 32 + 8 * fq;
; #pragma unroll
;         for (int ai = 0; ai < 2; ++ai)
; #pragma unroll
;             for (int m = 0; m < 4; ++m) {
;                 const int t = rowb + ai * 128 + m * 16; float ss = 0.f;
;                 float* xr = X + (size_t)t * D + colb; bf16_t* xbr = XB + (size_t)t * D + colb;
;                 if (GLU) {
;                     f32x4 y0, y1;
; #pragma unroll
;                     for (int jj = 0; jj < 4; ++jj) { y0[jj] = acc[ai][0][m][0][jj] * sigmoid_f(acc[ai][1][m][0][jj]); y1[jj] = acc[ai][0][m][1][jj] * sigmoid_f(acc[ai][1][m][1][jj]); }
;                     const f32x4 x0 = *(const f32x4*)xr + y0, x1 = *(const f32x4*)(xr + 4) + y1;
;                     if (!dry) { *(f32x4*)xr = x0; *(f32x4*)(xr + 4) = x1; store8bf(xbr, x0, x1); }
;                     ss += (x0[0] * x0[0] + x0[1] * x0[1]) + (x0[2] * x0[2] + x0[3] * x0[3]) + (x1[0] * x1[0] + x1[1] * x1[1]) + (x1[2] * x1[2] + x1[3] * x1[3]);
;                 } else {
; #pragma unroll
;                     for (int bj = 0; bj < 2; ++bj) {
;                         const f32x4 x0 = *(const f32x4*)(xr + bj * 128) + acc[ai][bj][m][0], x1 = *(const f32x4*)(xr + bj * 128 + 4) + acc[ai][bj][m][1];
;                         if (!dry) { *(f32x4*)(xr + bj * 128) = x0; *(f32x4*)(xr + bj * 128 + 4) = x1; store8bf(xbr + bj * 128, x0, x1); }
;                         ss += (x0[0] * x0[0] + x0[1] * x0[1]) + (x0[2] * x0[2] + x0[3] * x0[3]) + (x1[0] * x1[0] + x1[1] * x1[1]) + (x1[2] * x1[2] + x1[3] * x1[3]);
;                     }
;                 }
;                 ss += __shfl_xor(ss, 16); ss += __shfl_xor(ss, 32);
;                 if (fq == 0 && !dry) rsp_next[(size_t)t * 64 + u.pn * 4 + wc] = ss;
;             }
.LBB0_898:
	s_or_b64 exec, exec, s[4:5]
	v_or_b32_e32 v146, 16, v144
	s_waitcnt lgkmcnt(0)
	v_ashrrev_i32_e32 v147, 31, v146
	v_lshlrev_b64 v[154:155], 13, v[146:147]
	v_lshl_add_u64 v[166:167], v[142:143], 0, v[154:155]
	v_lshlrev_b64 v[154:155], 12, v[146:147]
	v_lshl_add_u64 v[168:169], v[140:141], 0, v[154:155]
	s_waitcnt vmcnt(18)
	v_mov_b64_e32 v[154:155], v[186:187]
	v_mov_b64_e32 v[156:157], v[188:189]
	v_mov_b64_e32 v[158:159], v[196:197]
	v_mov_b64_e32 v[160:161], v[198:199]
	v_pk_add_f32 v[156:157], v[114:115], v[156:157]
	v_pk_add_f32 v[158:159], v[116:117], v[158:159]
	v_pk_add_f32 v[160:161], v[118:119], v[160:161]
	v_mul_f32_e32 v145, v159, v159
	v_pk_add_f32 v[154:155], v[112:113], v[154:155]
	global_store_dwordx4 v[166:167], v[158:161], off
	global_store_dwordx4 v[166:167], v[154:157], off offset:16
	s_mov_b32 s100, 0x100200
	v_lshl_add_u64 v[190:191], v[216:217], 0, s[100:101]
	global_load_dwordx4 v[186:189], v[190:191], off offset:16
	global_load_dwordx4 v[196:199], v[190:191], off
	v_cvt_pk_bf16_f32 v162, v158, v159
	v_fmac_f32_e32 v145, v158, v158
	v_mul_f32_e32 v158, v161, v161
	v_cvt_pk_bf16_f32 v164, v154, v155
	v_fmac_f32_e32 v158, v160, v160
	v_mul_f32_e32 v155, v155, v155
	v_cvt_pk_bf16_f32 v163, v160, v161
	v_cvt_pk_bf16_f32 v165, v156, v157
	v_add_f32_e32 v145, v145, v158
	v_fmac_f32_e32 v155, v154, v154
	v_mul_f32_e32 v154, v157, v157
	global_store_dwordx4 v[168:169], v[162:165], off
	v_add_f32_e32 v145, v145, v155
	v_fmac_f32_e32 v154, v156, v156
	v_add_f32_e32 v145, v154, v145
	s_waitcnt vmcnt(21)
	v_mov_b64_e32 v[154:155], v[200:201]
	v_mov_b64_e32 v[156:157], v[202:203]
	v_mov_b64_e32 v[158:159], v[204:205]
	v_mov_b64_e32 v[160:161], v[206:207]
	v_pk_add_f32 v[156:157], v[90:91], v[156:157]
	v_pk_add_f32 v[160:161], v[94:95], v[160:161]
	v_pk_add_f32 v[158:159], v[92:93], v[158:159]
	v_pk_add_f32 v[154:155], v[88:89], v[154:155]
	global_store_dwordx4 v[166:167], v[158:161], off offset:512
	global_store_dwordx4 v[166:167], v[154:157], off offset:528
	s_mov_b32 s100, 0x120000
	v_lshl_add_u64 v[190:191], v[216:217], 0, s[100:101]
	global_load_dwordx4 v[200:203], v[190:191], off offset:16
	global_load_dwordx4 v[204:207], v[190:191], off
	v_cvt_pk_bf16_f32 v162, v158, v159
	v_mul_f32_e32 v159, v159, v159
	v_fmac_f32_e32 v159, v158, v158
	v_mul_f32_e32 v158, v161, v161
	v_cvt_pk_bf16_f32 v164, v154, v155
	v_fmac_f32_e32 v158, v160, v160
	v_mul_f32_e32 v155, v155, v155
	v_add_f32_e32 v158, v159, v158
	v_fmac_f32_e32 v155, v154, v154
	v_add_f32_e32 v154, v158, v155
	v_mul_f32_e32 v155, v157, v157
	v_fmac_f32_e32 v155, v156, v156
	v_add_f32_e32 v154, v155, v154
	v_add_f32_e32 v145, v145, v154
	ds_bpermute_b32 v154, v153, v145
	v_cvt_pk_bf16_f32 v163, v160, v161
	v_cvt_pk_bf16_f32 v165, v156, v157
	global_store_dwordx4 v[168:169], v[162:165], off offset:256
	s_waitcnt lgkmcnt(0)
	v_add_f32_e32 v145, v145, v154
	ds_bpermute_b32 v154, v139, v145
	s_and_saveexec_b64 s[4:5], s[6:7]
	s_cbranch_execz .LBB0_900
	s_lshl_b32 s14, s10, 2
	v_lshlrev_b64 v[146:147], 8, v[146:147]
	s_ashr_i32 s15, s14, 31
	v_lshl_add_u64 v[146:147], s[18:19], 0, v[146:147]
	v_lshl_add_u64 v[146:147], s[14:15], 2, v[146:147]
	s_lshl_b32 s68, s64, 2
	s_waitcnt lgkmcnt(0)
	v_add_f32_e32 v145, v145, v154
	v_lshl_add_u64 v[146:147], v[146:147], 0, s[68:69]
	global_store_dword v[146:147], v145, off
.LBB0_900:
	s_or_b64 exec, exec, s[4:5]
	v_or_b32_e32 v146, 32, v144
	v_ashrrev_i32_e32 v147, 31, v146
	s_waitcnt lgkmcnt(0)
	v_lshlrev_b64 v[154:155], 13, v[146:147]
	v_lshl_add_u64 v[166:167], v[142:143], 0, v[154:155]
	v_lshlrev_b64 v[154:155], 12, v[146:147]
	v_lshl_add_u64 v[168:169], v[140:141], 0, v[154:155]
	s_waitcnt vmcnt(24)
	v_mov_b64_e32 v[154:155], v[208:209]
	v_mov_b64_e32 v[156:157], v[210:211]
	v_mov_b64_e32 v[158:159], v[212:213]
	v_mov_b64_e32 v[160:161], v[214:215]
	v_pk_add_f32 v[156:157], v[98:99], v[156:157]
	v_pk_add_f32 v[158:159], v[100:101], v[158:159]
	v_pk_add_f32 v[160:161], v[102:103], v[160:161]
	v_mul_f32_e32 v145, v159, v159
	v_pk_add_f32 v[154:155], v[96:97], v[154:155]
	global_store_dwordx4 v[166:167], v[158:161], off
	global_store_dwordx4 v[166:167], v[154:157], off offset:16
	s_mov_b32 s100, 0x120200
	v_lshl_add_u64 v[190:191], v[216:217], 0, s[100:101]
	global_load_dwordx4 v[208:211], v[190:191], off offset:16
	global_load_dwordx4 v[212:215], v[190:191], off
	v_cvt_pk_bf16_f32 v162, v158, v159
	v_fmac_f32_e32 v145, v158, v158
	v_mul_f32_e32 v158, v161, v161
	v_cvt_pk_bf16_f32 v164, v154, v155
	v_fmac_f32_e32 v158, v160, v160
	v_mul_f32_e32 v155, v155, v155
	v_cvt_pk_bf16_f32 v163, v160, v161
	v_cvt_pk_bf16_f32 v165, v156, v157
	v_add_f32_e32 v145, v145, v158
	v_fmac_f32_e32 v155, v154, v154
	v_mul_f32_e32 v154, v157, v157
	global_store_dwordx4 v[168:169], v[162:165], off
	v_add_f32_e32 v145, v145, v155
	v_fmac_f32_e32 v154, v156, v156
	v_add_f32_e32 v145, v154, v145
	s_waitcnt vmcnt(27)
	v_mov_b64_e32 v[154:155], v[224:225]
	v_mov_b64_e32 v[156:157], v[226:227]
	v_mov_b64_e32 v[158:159], v[236:237]
	v_mov_b64_e32 v[160:161], v[238:239]
	v_pk_add_f32 v[156:157], v[74:75], v[156:157]
	v_pk_add_f32 v[160:161], v[78:79], v[160:161]
	v_pk_add_f32 v[158:159], v[76:77], v[158:159]
	v_pk_add_f32 v[154:155], v[72:73], v[154:155]
	global_store_dwordx4 v[166:167], v[158:161], off offset:512
	global_store_dwordx4 v[166:167], v[154:157], off offset:528
	s_mov_b32 s100, 0x140000
	v_lshl_add_u64 v[190:191], v[216:217], 0, s[100:101]
	global_load_dwordx4 v[224:227], v[190:191], off offset:16
	global_load_dwordx4 v[236:239], v[190:191], off
	v_cvt_pk_bf16_f32 v162, v158, v159
	v_mul_f32_e32 v159, v159, v159
	v_fmac_f32_e32 v159, v158, v158
	v_mul_f32_e32 v158, v161, v161
	v_cvt_pk_bf16_f32 v164, v154, v155
	v_fmac_f32_e32 v158, v160, v160
	v_mul_f32_e32 v155, v155, v155
	v_add_f32_e32 v158, v159, v158
	v_fmac_f32_e32 v155, v154, v154
	v_add_f32_e32 v154, v158, v155
	v_mul_f32_e32 v155, v157, v157
	v_fmac_f32_e32 v155, v156, v156
	v_add_f32_e32 v154, v155, v154
	v_add_f32_e32 v145, v145, v154
	ds_bpermute_b32 v154, v153, v145
	v_cvt_pk_bf16_f32 v163, v160, v161
	v_cvt_pk_bf16_f32 v165, v156, v157
	global_store_dwordx4 v[168:169], v[162:165], off offset:256
	s_waitcnt lgkmcnt(0)
	v_add_f32_e32 v145, v145, v154
	ds_bpermute_b32 v154, v139, v145
	s_and_saveexec_b64 s[4:5], s[6:7]
	s_cbranch_execz .LBB0_902
	s_lshl_b32 s14, s10, 2
	v_lshlrev_b64 v[146:147], 8, v[146:147]
	s_ashr_i32 s15, s14, 31
	v_lshl_add_u64 v[146:147], s[18:19], 0, v[146:147]
	v_lshl_add_u64 v[146:147], s[14:15], 2, v[146:147]
	s_lshl_b32 s68, s64, 2
	s_waitcnt lgkmcnt(0)
	v_add_f32_e32 v145, v145, v154
	v_lshl_add_u64 v[146:147], v[146:147], 0, s[68:69]
	global_store_dword v[146:147], v145, off
; __device__ __forceinline__ void store8bf(bf16_t* p, f32x4 a, f32x4 b) { u32x4 w; w.x = pk2(a[0], a[1]); w.y = pk2(a[2], a[3]); w.z = pk2(b[0], b[1]); w.w = pk2(b[2], b[3]); *(u32x4*)p = w; }
; __device__ __forceinline__ float sigmoid_f(float v) { return 1.0f / (1.0f + __expf(-v)); }
;     __device__ __forceinline__ void operator()(const f32x4 (&acc)[2][2][4][2], const pg8::Unit& u, int wr, int wc, int fr, int fq) const {
;     ...
;         const int rowb = u.pm * 256 + wr * 64 + fr, colb = u.pn * (GLU ? 128 : 256) + wc * 32 + 8 * fq;
; #pragma unroll
;         for (int ai = 0; ai < 2; ++ai)
; #pragma unroll
;             for (int m = 0; m < 4; ++m) {
;                 const int t = rowb + ai * 128 + m * 16; float ss = 0.f;
;                 float* xr = X + (size_t)t * D + colb; bf16_t* xbr = XB + (size_t)t * D + colb;
;                 if (GLU) {
;                     f32x4 y0, y1;
; #pragma unroll
;                     for (int jj = 0; jj < 4; ++jj) { y0[jj] = acc[ai][0][m][0][jj] * sigmoid_f(acc[ai][1][m][0][jj]); y1[jj] = acc[ai][0][m][1][jj] * sigmoid_f(acc[ai][1][m][1][jj]); }
;                     const f32x4 x0 = *(const f32x4*)xr + y0, x1 = *(const f32x4*)(xr + 4) + y1;
;                     if (!dry) { *(f32x4*)xr = x0; *(f32x4*)(xr + 4) = x1; store8bf(xbr, x0, x1); }
;                     ss += (x0[0] * x0[0] + x0[1] * x0[1]) + (x0[2] * x0[2] + x0[3] * x0[3]) + (x1[0] * x1[0] + x1[1] * x1[1]) + (x1[2] * x1[2] + x1[3] * x1[3]);
;                 } else {
; #pragma unroll
;                     for (int bj = 0; bj < 2; ++bj) {
;                         const f32x4 x0 = *(const f32x4*)(xr + bj * 128) + acc[ai][bj][m][0], x1 = *(const f32x4*)(xr + bj * 128 + 4) + acc[ai][bj][m][1];
;                         if (!dry) { *(f32x4*)(xr + bj * 128) = x0; *(f32x4*)(xr + bj * 128 + 4) = x1; store8bf(xbr + bj * 128, x0, x1); }
;                         ss += (x0[0] * x0[0] + x0[1] * x0[1]) + (x0[2] * x0[2] + x0[3] * x0[3]) + (x1[0] * x1[0] + x1[1] * x1[1]) + (x1[2] * x1[2] + x1[3] * x1[3]);
;                     }
;                 }
;                 ss += __shfl_xor(ss, 16); ss += __shfl_xor(ss, 32);
;                 if (fq == 0 && !dry) rsp_next[(size_t)t * 64 + u.pn * 4 + wc] = ss;
;             }
.LBB0_902:
	s_or_b64 exec, exec, s[4:5]
	v_or_b32_e32 v146, 48, v144
	v_ashrrev_i32_e32 v147, 31, v146
	s_waitcnt lgkmcnt(0)
	v_lshlrev_b64 v[154:155], 13, v[146:147]
	v_lshl_add_u64 v[166:167], v[142:143], 0, v[154:155]
	v_lshlrev_b64 v[154:155], 12, v[146:147]
	v_lshl_add_u64 v[168:169], v[140:141], 0, v[154:155]
	s_waitcnt vmcnt(30)
	v_mov_b64_e32 v[154:155], v[240:241]
	v_mov_b64_e32 v[156:157], v[242:243]
	v_mov_b64_e32 v[158:159], v[244:245]
	v_mov_b64_e32 v[160:161], v[246:247]
	v_pk_add_f32 v[156:157], v[82:83], v[156:157]
	v_pk_add_f32 v[158:159], v[84:85], v[158:159]
	v_pk_add_f32 v[160:161], v[86:87], v[160:161]
	v_mul_f32_e32 v145, v159, v159
	v_pk_add_f32 v[154:155], v[80:81], v[154:155]
	global_store_dwordx4 v[166:167], v[158:161], off
	global_store_dwordx4 v[166:167], v[154:157], off offset:16
	s_mov_b32 s100, 0x140200
	v_lshl_add_u64 v[190:191], v[216:217], 0, s[100:101]
	global_load_dwordx4 v[240:243], v[190:191], off offset:16
	global_load_dwordx4 v[244:247], v[190:191], off
	v_cvt_pk_bf16_f32 v162, v158, v159
	v_fmac_f32_e32 v145, v158, v158
	v_mul_f32_e32 v158, v161, v161
	v_cvt_pk_bf16_f32 v164, v154, v155
	v_fmac_f32_e32 v158, v160, v160
	v_mul_f32_e32 v155, v155, v155
	v_cvt_pk_bf16_f32 v163, v160, v161
	v_cvt_pk_bf16_f32 v165, v156, v157
	v_add_f32_e32 v145, v145, v158
	v_fmac_f32_e32 v155, v154, v154
	v_mul_f32_e32 v154, v157, v157
	global_store_dwordx4 v[168:169], v[162:165], off
	v_add_f32_e32 v145, v145, v155
	v_fmac_f32_e32 v154, v156, v156
	v_add_f32_e32 v145, v154, v145
	s_waitcnt vmcnt(31)
	v_mov_b64_e32 v[154:155], v[170:171]
	v_mov_b64_e32 v[156:157], v[172:173]
	v_mov_b64_e32 v[158:159], v[174:175]
	v_mov_b64_e32 v[160:161], v[176:177]
	v_pk_add_f32 v[156:157], v[66:67], v[156:157]
	v_pk_add_f32 v[160:161], v[70:71], v[160:161]
	v_pk_add_f32 v[158:159], v[68:69], v[158:159]
	v_pk_add_f32 v[154:155], v[64:65], v[154:155]
	global_store_dwordx4 v[166:167], v[158:161], off offset:512
	global_store_dwordx4 v[166:167], v[154:157], off offset:528
	s_mov_b32 s100, 0x160000
	v_lshl_add_u64 v[190:191], v[216:217], 0, s[100:101]
	global_load_dwordx4 v[170:173], v[190:191], off offset:16
	global_load_dwordx4 v[174:177], v[190:191], off
	v_cvt_pk_bf16_f32 v162, v158, v159
	v_mul_f32_e32 v159, v159, v159
	v_fmac_f32_e32 v159, v158, v158
	v_mul_f32_e32 v158, v161, v161
	v_cvt_pk_bf16_f32 v164, v154, v155
	v_fmac_f32_e32 v158, v160, v160
	v_mul_f32_e32 v155, v155, v155
	v_add_f32_e32 v158, v159, v158
	v_fmac_f32_e32 v155, v154, v154
	v_add_f32_e32 v154, v158, v155
	v_mul_f32_e32 v155, v157, v157
	v_fmac_f32_e32 v155, v156, v156
	v_add_f32_e32 v154, v155, v154
	v_add_f32_e32 v145, v145, v154
	ds_bpermute_b32 v154, v153, v145
	v_cvt_pk_bf16_f32 v163, v160, v161
	v_cvt_pk_bf16_f32 v165, v156, v157
	global_store_dwordx4 v[168:169], v[162:165], off offset:256
	s_waitcnt lgkmcnt(0)
	v_add_f32_e32 v145, v145, v154
	ds_bpermute_b32 v154, v139, v145
	s_and_saveexec_b64 s[4:5], s[6:7]
	s_cbranch_execz .LBB0_904
	s_lshl_b32 s14, s10, 2
	v_lshlrev_b64 v[146:147], 8, v[146:147]
	s_ashr_i32 s15, s14, 31
	v_lshl_add_u64 v[146:147], s[18:19], 0, v[146:147]
	v_lshl_add_u64 v[146:147], s[14:15], 2, v[146:147]
	s_lshl_b32 s68, s64, 2
	s_waitcnt lgkmcnt(0)
	v_add_f32_e32 v145, v145, v154
	v_lshl_add_u64 v[146:147], v[146:147], 0, s[68:69]
	global_store_dword v[146:147], v145, off
.LBB0_904:
	s_or_b64 exec, exec, s[4:5]
	v_add_u32_e32 v146, 0x80, v144
	v_ashrrev_i32_e32 v147, 31, v146
	s_waitcnt lgkmcnt(0)
	v_lshlrev_b64 v[154:155], 13, v[146:147]
	v_lshl_add_u64 v[166:167], v[142:143], 0, v[154:155]
	v_lshlrev_b64 v[154:155], 12, v[146:147]
	v_lshl_add_u64 v[168:169], v[140:141], 0, v[154:155]
	s_waitcnt vmcnt(31)
	v_mov_b64_e32 v[154:155], v[178:179]
	v_mov_b64_e32 v[156:157], v[180:181]
	v_mov_b64_e32 v[158:159], v[182:183]
	v_mov_b64_e32 v[160:161], v[184:185]
	v_pk_add_f32 v[156:157], v[58:59], v[156:157]
	v_pk_add_f32 v[158:159], v[60:61], v[158:159]
	v_pk_add_f32 v[160:161], v[62:63], v[160:161]
	v_mul_f32_e32 v145, v159, v159
	v_pk_add_f32 v[154:155], v[56:57], v[154:155]
	global_store_dwordx4 v[166:167], v[158:161], off
	global_store_dwordx4 v[166:167], v[154:157], off offset:16
	s_mov_b32 s100, 0x160200
	v_lshl_add_u64 v[190:191], v[216:217], 0, s[100:101]
	global_load_dwordx4 v[178:181], v[190:191], off offset:16
	global_load_dwordx4 v[182:185], v[190:191], off
	v_cvt_pk_bf16_f32 v162, v158, v159
	v_fmac_f32_e32 v145, v158, v158
	v_mul_f32_e32 v158, v161, v161
	v_cvt_pk_bf16_f32 v164, v154, v155
	v_fmac_f32_e32 v158, v160, v160
	v_mul_f32_e32 v155, v155, v155
	v_cvt_pk_bf16_f32 v163, v160, v161
	v_cvt_pk_bf16_f32 v165, v156, v157
	v_add_f32_e32 v145, v145, v158
	v_fmac_f32_e32 v155, v154, v154
	v_mul_f32_e32 v154, v157, v157
	global_store_dwordx4 v[168:169], v[162:165], off
	v_add_f32_e32 v145, v145, v155
	v_fmac_f32_e32 v154, v156, v156
	v_add_f32_e32 v145, v154, v145
	s_waitcnt vmcnt(31)
	v_mov_b64_e32 v[154:155], v[186:187]
	v_mov_b64_e32 v[156:157], v[188:189]
	v_mov_b64_e32 v[158:159], v[196:197]
	v_mov_b64_e32 v[160:161], v[198:199]
	v_pk_add_f32 v[156:157], v[42:43], v[156:157]
	v_pk_add_f32 v[160:161], v[46:47], v[160:161]
	v_pk_add_f32 v[158:159], v[44:45], v[158:159]
	v_pk_add_f32 v[154:155], v[40:41], v[154:155]
	global_store_dwordx4 v[166:167], v[158:161], off offset:512
	global_store_dwordx4 v[166:167], v[154:157], off offset:528
	v_cvt_pk_bf16_f32 v162, v158, v159
	v_mul_f32_e32 v159, v159, v159
	v_fmac_f32_e32 v159, v158, v158
	v_mul_f32_e32 v158, v161, v161
	v_cvt_pk_bf16_f32 v164, v154, v155
	v_fmac_f32_e32 v158, v160, v160
	v_mul_f32_e32 v155, v155, v155
	v_add_f32_e32 v158, v159, v158
	v_fmac_f32_e32 v155, v154, v154
	v_add_f32_e32 v154, v158, v155
	v_mul_f32_e32 v155, v157, v157
	v_fmac_f32_e32 v155, v156, v156
	v_add_f32_e32 v154, v155, v154
	v_add_f32_e32 v145, v145, v154
	ds_bpermute_b32 v154, v153, v145
	v_cvt_pk_bf16_f32 v163, v160, v161
	v_cvt_pk_bf16_f32 v165, v156, v157
	global_store_dwordx4 v[168:169], v[162:165], off offset:256
	s_waitcnt lgkmcnt(0)
	v_add_f32_e32 v145, v145, v154
	ds_bpermute_b32 v154, v139, v145
	s_and_saveexec_b64 s[4:5], s[6:7]
	s_cbranch_execz .LBB0_906
	s_lshl_b32 s14, s10, 2
	v_lshlrev_b64 v[146:147], 8, v[146:147]
	s_ashr_i32 s15, s14, 31
	v_lshl_add_u64 v[146:147], s[18:19], 0, v[146:147]
	v_lshl_add_u64 v[146:147], s[14:15], 2, v[146:147]
	s_lshl_b32 s68, s64, 2
	s_waitcnt lgkmcnt(0)
	v_add_f32_e32 v145, v145, v154
	v_lshl_add_u64 v[146:147], v[146:147], 0, s[68:69]
	global_store_dword v[146:147], v145, off
; __device__ __forceinline__ void store8bf(bf16_t* p, f32x4 a, f32x4 b) { u32x4 w; w.x = pk2(a[0], a[1]); w.y = pk2(a[2], a[3]); w.z = pk2(b[0], b[1]); w.w = pk2(b[2], b[3]); *(u32x4*)p = w; }
; __device__ __forceinline__ float sigmoid_f(float v) { return 1.0f / (1.0f + __expf(-v)); }
;     __device__ __forceinline__ void operator()(const f32x4 (&acc)[2][2][4][2], const pg8::Unit& u, int wr, int wc, int fr, int fq) const {
;     ...
;         const int rowb = u.pm * 256 + wr * 64 + fr, colb = u.pn * (GLU ? 128 : 256) + wc * 32 + 8 * fq;
; #pragma unroll
;         for (int ai = 0; ai < 2; ++ai)
; #pragma unroll
;             for (int m = 0; m < 4; ++m) {
;                 const int t = rowb + ai * 128 + m * 16; float ss = 0.f;
;                 float* xr = X + (size_t)t * D + colb; bf16_t* xbr = XB + (size_t)t * D + colb;
;                 if (GLU) {
;                     f32x4 y0, y1;
; #pragma unroll
;                     for (int jj = 0; jj < 4; ++jj) { y0[jj] = acc[ai][0][m][0][jj] * sigmoid_f(acc[ai][1][m][0][jj]); y1[jj] = acc[ai][0][m][1][jj] * sigmoid_f(acc[ai][1][m][1][jj]); }
;                     const f32x4 x0 = *(const f32x4*)xr + y0, x1 = *(const f32x4*)(xr + 4) + y1;
;                     if (!dry) { *(f32x4*)xr = x0; *(f32x4*)(xr + 4) = x1; store8bf(xbr, x0, x1); }
;                     ss += (x0[0] * x0[0] + x0[1] * x0[1]) + (x0[2] * x0[2] + x0[3] * x0[3]) + (x1[0] * x1[0] + x1[1] * x1[1]) + (x1[2] * x1[2] + x1[3] * x1[3]);
;                 } else {
; #pragma unroll
;                     for (int bj = 0; bj < 2; ++bj) {
;                         const f32x4 x0 = *(const f32x4*)(xr + bj * 128) + acc[ai][bj][m][0], x1 = *(const f32x4*)(xr + bj * 128 + 4) + acc[ai][bj][m][1];
;                         if (!dry) { *(f32x4*)(xr + bj * 128) = x0; *(f32x4*)(xr + bj * 128 + 4) = x1; store8bf(xbr + bj * 128, x0, x1); }
;                         ss += (x0[0] * x0[0] + x0[1] * x0[1]) + (x0[2] * x0[2] + x0[3] * x0[3]) + (x1[0] * x1[0] + x1[1] * x1[1]) + (x1[2] * x1[2] + x1[3] * x1[3]);
;                     }
;                 }
;                 ss += __shfl_xor(ss, 16); ss += __shfl_xor(ss, 32);
;                 if (fq == 0 && !dry) rsp_next[(size_t)t * 64 + u.pn * 4 + wc] = ss;
;             }
.LBB0_906:
	s_or_b64 exec, exec, s[4:5]
	v_add_u32_e32 v146, 0x90, v144
	v_ashrrev_i32_e32 v147, 31, v146
	s_waitcnt lgkmcnt(0)
	v_lshlrev_b64 v[154:155], 13, v[146:147]
	v_lshl_add_u64 v[166:167], v[142:143], 0, v[154:155]
	v_lshlrev_b64 v[154:155], 12, v[146:147]
	v_lshl_add_u64 v[168:169], v[140:141], 0, v[154:155]
	s_waitcnt vmcnt(29)
	v_mov_b64_e32 v[154:155], v[200:201]
	v_mov_b64_e32 v[156:157], v[202:203]
	v_mov_b64_e32 v[158:159], v[204:205]
	v_mov_b64_e32 v[160:161], v[206:207]
	v_pk_add_f32 v[156:157], v[50:51], v[156:157]
	v_pk_add_f32 v[158:159], v[52:53], v[158:159]
	v_pk_add_f32 v[160:161], v[54:55], v[160:161]
	v_mul_f32_e32 v145, v159, v159
	v_pk_add_f32 v[154:155], v[48:49], v[154:155]
	global_store_dwordx4 v[166:167], v[158:161], off
	global_store_dwordx4 v[166:167], v[154:157], off offset:16
	v_cvt_pk_bf16_f32 v162, v158, v159
	v_fmac_f32_e32 v145, v158, v158
	v_mul_f32_e32 v158, v161, v161
	v_cvt_pk_bf16_f32 v164, v154, v155
	v_fmac_f32_e32 v158, v160, v160
	v_mul_f32_e32 v155, v155, v155
	v_cvt_pk_bf16_f32 v163, v160, v161
	v_cvt_pk_bf16_f32 v165, v156, v157
	v_add_f32_e32 v145, v145, v158
	v_fmac_f32_e32 v155, v154, v154
	v_mul_f32_e32 v154, v157, v157
	global_store_dwordx4 v[168:169], v[162:165], off
	v_add_f32_e32 v145, v145, v155
	v_fmac_f32_e32 v154, v156, v156
	v_add_f32_e32 v145, v154, v145
	s_waitcnt vmcnt(27)
	v_mov_b64_e32 v[154:155], v[208:209]
	v_mov_b64_e32 v[156:157], v[210:211]
	v_mov_b64_e32 v[158:159], v[212:213]
	v_mov_b64_e32 v[160:161], v[214:215]
	v_pk_add_f32 v[156:157], v[26:27], v[156:157]
	v_pk_add_f32 v[160:161], v[30:31], v[160:161]
	v_pk_add_f32 v[158:159], v[28:29], v[158:159]
	v_pk_add_f32 v[154:155], v[24:25], v[154:155]
	global_store_dwordx4 v[166:167], v[158:161], off offset:512
	global_store_dwordx4 v[166:167], v[154:157], off offset:528
	v_cvt_pk_bf16_f32 v162, v158, v159
	v_mul_f32_e32 v159, v159, v159
	v_fmac_f32_e32 v159, v158, v158
	v_mul_f32_e32 v158, v161, v161
	v_cvt_pk_bf16_f32 v164, v154, v155
	v_fmac_f32_e32 v158, v160, v160
	v_mul_f32_e32 v155, v155, v155
	v_add_f32_e32 v158, v159, v158
	v_fmac_f32_e32 v155, v154, v154
	v_add_f32_e32 v154, v158, v155
	v_mul_f32_e32 v155, v157, v157
	v_fmac_f32_e32 v155, v156, v156
	v_add_f32_e32 v154, v155, v154
	v_add_f32_e32 v145, v145, v154
	ds_bpermute_b32 v154, v153, v145
	v_cvt_pk_bf16_f32 v163, v160, v161
	v_cvt_pk_bf16_f32 v165, v156, v157
	global_store_dwordx4 v[168:169], v[162:165], off offset:256
	s_waitcnt lgkmcnt(0)
	v_add_f32_e32 v145, v145, v154
	ds_bpermute_b32 v154, v139, v145
	s_and_saveexec_b64 s[4:5], s[6:7]
	s_cbranch_execz .LBB0_908
	s_lshl_b32 s14, s10, 2
	v_lshlrev_b64 v[146:147], 8, v[146:147]
	s_ashr_i32 s15, s14, 31
	v_lshl_add_u64 v[146:147], s[18:19], 0, v[146:147]
	v_lshl_add_u64 v[146:147], s[14:15], 2, v[146:147]
	s_lshl_b32 s68, s64, 2
	s_waitcnt lgkmcnt(0)
	v_add_f32_e32 v145, v145, v154
	v_lshl_add_u64 v[146:147], v[146:147], 0, s[68:69]
	global_store_dword v[146:147], v145, off
; __device__ __forceinline__ void store8bf(bf16_t* p, f32x4 a, f32x4 b) { u32x4 w; w.x = pk2(a[0], a[1]); w.y = pk2(a[2], a[3]); w.z = pk2(b[0], b[1]); w.w = pk2(b[2], b[3]); *(u32x4*)p = w; }
; __device__ __forceinline__ float sigmoid_f(float v) { return 1.0f / (1.0f + __expf(-v)); }
;     __device__ __forceinline__ void operator()(const f32x4 (&acc)[2][2][4][2], const pg8::Unit& u, int wr, int wc, int fr, int fq) const {
;     ...
;         const int rowb = u.pm * 256 + wr * 64 + fr, colb = u.pn * (GLU ? 128 : 256) + wc * 32 + 8 * fq;
; #pragma unroll
;         for (int ai = 0; ai < 2; ++ai)
; #pragma unroll
;             for (int m = 0; m < 4; ++m) {
;                 const int t = rowb + ai * 128 + m * 16; float ss = 0.f;
;                 float* xr = X + (size_t)t * D + colb; bf16_t* xbr = XB + (size_t)t * D + colb;
;                 if (GLU) {
;                     f32x4 y0, y1;
; #pragma unroll
;                     for (int jj = 0; jj < 4; ++jj) { y0[jj] = acc[ai][0][m][0][jj] * sigmoid_f(acc[ai][1][m][0][jj]); y1[jj] = acc[ai][0][m][1][jj] * sigmoid_f(acc[ai][1][m][1][jj]); }
;                     const f32x4 x0 = *(const f32x4*)xr + y0, x1 = *(const f32x4*)(xr + 4) + y1;
;                     if (!dry) { *(f32x4*)xr = x0; *(f32x4*)(xr + 4) = x1; store8bf(xbr, x0, x1); }
;                     ss += (x0[0] * x0[0] + x0[1] * x0[1]) + (x0[2] * x0[2] + x0[3] * x0[3]) + (x1[0] * x1[0] + x1[1] * x1[1]) + (x1[2] * x1[2] + x1[3] * x1[3]);
;                 } else {
; #pragma unroll
;                     for (int bj = 0; bj < 2; ++bj) {
;                         const f32x4 x0 = *(const f32x4*)(xr + bj * 128) + acc[ai][bj][m][0], x1 = *(const f32x4*)(xr + bj * 128 + 4) + acc[ai][bj][m][1];
;                         if (!dry) { *(f32x4*)(xr + bj * 128) = x0; *(f32x4*)(xr + bj * 128 + 4) = x1; store8bf(xbr + bj * 128, x0, x1); }
;                         ss += (x0[0] * x0[0] + x0[1] * x0[1]) + (x0[2] * x0[2] + x0[3] * x0[3]) + (x1[0] * x1[0] + x1[1] * x1[1]) + (x1[2] * x1[2] + x1[3] * x1[3]);
;                     }
;                 }
;                 ss += __shfl_xor(ss, 16); ss += __shfl_xor(ss, 32);
;                 if (fq == 0 && !dry) rsp_next[(size_t)t * 64 + u.pn * 4 + wc] = ss;
;             }
.LBB0_908:
	s_or_b64 exec, exec, s[4:5]
	v_add_u32_e32 v146, 0xa0, v144
	v_ashrrev_i32_e32 v147, 31, v146
	s_waitcnt lgkmcnt(0)
	v_lshlrev_b64 v[154:155], 13, v[146:147]
	v_lshl_add_u64 v[166:167], v[142:143], 0, v[154:155]
	v_lshlrev_b64 v[154:155], 12, v[146:147]
	v_lshl_add_u64 v[168:169], v[140:141], 0, v[154:155]
	s_waitcnt vmcnt(25)
	v_mov_b64_e32 v[154:155], v[224:225]
	v_mov_b64_e32 v[156:157], v[226:227]
	v_mov_b64_e32 v[158:159], v[236:237]
	v_mov_b64_e32 v[160:161], v[238:239]
	v_pk_add_f32 v[156:157], v[34:35], v[156:157]
	v_pk_add_f32 v[158:159], v[36:37], v[158:159]
	v_pk_add_f32 v[160:161], v[38:39], v[160:161]
	v_mul_f32_e32 v145, v159, v159
	v_pk_add_f32 v[154:155], v[32:33], v[154:155]
	global_store_dwordx4 v[166:167], v[158:161], off
	global_store_dwordx4 v[166:167], v[154:157], off offset:16
	v_cvt_pk_bf16_f32 v162, v158, v159
	v_fmac_f32_e32 v145, v158, v158
	v_mul_f32_e32 v158, v161, v161
	v_cvt_pk_bf16_f32 v164, v154, v155
	v_fmac_f32_e32 v158, v160, v160
	v_mul_f32_e32 v155, v155, v155
	v_cvt_pk_bf16_f32 v163, v160, v161
	v_cvt_pk_bf16_f32 v165, v156, v157
	v_add_f32_e32 v145, v145, v158
	v_fmac_f32_e32 v155, v154, v154
	v_mul_f32_e32 v154, v157, v157
	global_store_dwordx4 v[168:169], v[162:165], off
	v_add_f32_e32 v145, v145, v155
	v_fmac_f32_e32 v154, v156, v156
	v_add_f32_e32 v145, v154, v145
	s_waitcnt vmcnt(23)
	v_mov_b64_e32 v[154:155], v[240:241]
	v_mov_b64_e32 v[156:157], v[242:243]
	v_mov_b64_e32 v[158:159], v[244:245]
	v_mov_b64_e32 v[160:161], v[246:247]
	v_pk_add_f32 v[156:157], v[10:11], v[156:157]
	v_pk_add_f32 v[160:161], v[14:15], v[160:161]
	v_pk_add_f32 v[158:159], v[12:13], v[158:159]
	v_pk_add_f32 v[154:155], v[8:9], v[154:155]
	global_store_dwordx4 v[166:167], v[158:161], off offset:512
	global_store_dwordx4 v[166:167], v[154:157], off offset:528
	v_cvt_pk_bf16_f32 v162, v158, v159
	v_mul_f32_e32 v159, v159, v159
	v_fmac_f32_e32 v159, v158, v158
	v_mul_f32_e32 v158, v161, v161
	v_cvt_pk_bf16_f32 v164, v154, v155
	v_fmac_f32_e32 v158, v160, v160
	v_mul_f32_e32 v155, v155, v155
	v_add_f32_e32 v158, v159, v158
	v_fmac_f32_e32 v155, v154, v154
	v_add_f32_e32 v154, v158, v155
	v_mul_f32_e32 v155, v157, v157
	v_fmac_f32_e32 v155, v156, v156
	v_add_f32_e32 v154, v155, v154
	v_add_f32_e32 v145, v145, v154
	ds_bpermute_b32 v154, v153, v145
	v_cvt_pk_bf16_f32 v163, v160, v161
	v_cvt_pk_bf16_f32 v165, v156, v157
	global_store_dwordx4 v[168:169], v[162:165], off offset:256
	s_waitcnt lgkmcnt(0)
	v_add_f32_e32 v145, v145, v154
	ds_bpermute_b32 v154, v139, v145
	s_and_saveexec_b64 s[4:5], s[6:7]
	s_cbranch_execz .LBB0_910
	s_lshl_b32 s14, s10, 2
	v_lshlrev_b64 v[146:147], 8, v[146:147]
	s_ashr_i32 s15, s14, 31
	v_lshl_add_u64 v[146:147], s[18:19], 0, v[146:147]
	v_lshl_add_u64 v[146:147], s[14:15], 2, v[146:147]
	s_lshl_b32 s68, s64, 2
	s_waitcnt lgkmcnt(0)
	v_add_f32_e32 v145, v145, v154
	v_lshl_add_u64 v[146:147], v[146:147], 0, s[68:69]
	global_store_dword v[146:147], v145, off
.LBB0_910:
	s_or_b64 exec, exec, s[4:5]
	v_add_u32_e32 v144, 0xb0, v144
	v_ashrrev_i32_e32 v145, 31, v144
	v_lshlrev_b64 v[146:147], 13, v[144:145]
	v_lshl_add_u64 v[146:147], v[142:143], 0, v[146:147]
	v_lshlrev_b64 v[142:143], 12, v[144:145]
	v_lshl_add_u64 v[162:163], v[140:141], 0, v[142:143]
	s_waitcnt vmcnt(21)
	v_mov_b64_e32 v[140:141], v[170:171]
	v_mov_b64_e32 v[142:143], v[172:173]
	v_mov_b64_e32 v[154:155], v[174:175]
	v_mov_b64_e32 v[156:157], v[176:177]
	s_waitcnt lgkmcnt(0)
	v_pk_add_f32 v[142:143], v[18:19], v[142:143]
	v_pk_add_f32 v[156:157], v[22:23], v[156:157]
	v_pk_add_f32 v[154:155], v[20:21], v[154:155]
	v_pk_add_f32 v[140:141], v[16:17], v[140:141]
	global_store_dwordx4 v[146:147], v[154:157], off
	global_store_dwordx4 v[146:147], v[140:143], off offset:16
	v_cvt_pk_bf16_f32 v158, v154, v155
	v_mul_f32_e32 v155, v155, v155
	v_fmac_f32_e32 v155, v154, v154
	v_mul_f32_e32 v154, v157, v157
	v_cvt_pk_bf16_f32 v160, v140, v141
	v_fmac_f32_e32 v154, v156, v156
	v_mul_f32_e32 v141, v141, v141
	v_add_f32_e32 v154, v155, v154
	v_fmac_f32_e32 v141, v140, v140
	v_cvt_pk_bf16_f32 v159, v156, v157
	v_cvt_pk_bf16_f32 v161, v142, v143
	v_add_f32_e32 v140, v154, v141
	v_mul_f32_e32 v141, v143, v143
	global_store_dwordx4 v[162:163], v[158:161], off
	v_fmac_f32_e32 v141, v142, v142
	v_add_f32_e32 v164, v141, v140
	s_waitcnt vmcnt(19)
	v_mov_b64_e32 v[140:141], v[178:179]
	v_mov_b64_e32 v[142:143], v[180:181]
	v_mov_b64_e32 v[154:155], v[182:183]
	v_mov_b64_e32 v[156:157], v[184:185]
	v_pk_add_f32 v[142:143], v[2:3], v[142:143]
	v_pk_add_f32 v[156:157], v[6:7], v[156:157]
	v_pk_add_f32 v[154:155], v[4:5], v[154:155]
	v_pk_add_f32 v[140:141], v[0:1], v[140:141]
	global_store_dwordx4 v[146:147], v[154:157], off offset:512
	global_store_dwordx4 v[146:147], v[140:143], off offset:528
	v_mul_f32_e32 v146, v155, v155
	v_mul_f32_e32 v147, v157, v157
	v_cvt_pk_bf16_f32 v160, v140, v141
	v_fmac_f32_e32 v146, v154, v154
	v_fmac_f32_e32 v147, v156, v156
	v_mul_f32_e32 v141, v141, v141
	v_add_f32_e32 v146, v146, v147
	v_fmac_f32_e32 v141, v140, v140
	v_add_f32_e32 v140, v146, v141
	v_mul_f32_e32 v141, v143, v143
	v_fmac_f32_e32 v141, v142, v142
	v_add_f32_e32 v140, v141, v140
	v_add_f32_e32 v140, v164, v140
	ds_bpermute_b32 v141, v153, v140
	v_cvt_pk_bf16_f32 v158, v154, v155
	v_cvt_pk_bf16_f32 v159, v156, v157
	v_cvt_pk_bf16_f32 v161, v142, v143
	global_store_dwordx4 v[162:163], v[158:161], off offset:256
	s_waitcnt lgkmcnt(0)
	v_add_f32_e32 v140, v140, v141
	ds_bpermute_b32 v139, v139, v140
	s_and_saveexec_b64 s[4:5], s[6:7]
	s_cbranch_execz .LBB0_912
	s_waitcnt lgkmcnt(0)
	v_add_f32_e32 v139, v140, v139
	s_lshl_b32 s14, s10, 2
	v_lshlrev_b64 v[140:141], 8, v[144:145]
	s_ashr_i32 s15, s14, 31
	v_lshl_add_u64 v[140:141], s[18:19], 0, v[140:141]
	v_lshl_add_u64 v[140:141], s[14:15], 2, v[140:141]
	s_lshl_b32 s68, s64, 2
	v_lshl_add_u64 v[140:141], v[140:141], 0, s[68:69]
	global_store_dword v[140:141], v139, off
